# in-proj: n-tiles per workgroup from a table so every class gets one heavy-epilogue q/k tile, one plain-norm q/k tile and two cheap tiles (was up to three heavy per class)
# speedup vs baseline: 1.0143x; 1.0143x over previous
; DI void inproj_phase(const Params& p, int l, char* smem) {
;     ...
;     for (int it = 0;; ++it) {
;         int mtile, nt;
;         if (xmap) {
;             if (it >= 4 || xj >= 63) break;
;             mtile = 9 * xcd + (xj % 9); nt = 7 * it + (xj / 9);
;         } else {
;             const int tile = blockIdx.x + it * gridDim.x;
;             if (tile >= MT * NT) break;
;             mtile = tile / NT; nt = tile % NT;
;         }
;         const int n0 = nt * 128;
.LBB0_192:
	s_mov_b64 s[4:5], 0
	s_cbranch_execz .LBB0_191
	s_cmp_lt_u32 s98, 4
	v_readlane_b32 s8, v255, 26
	s_cselect_b64 s[6:7], -1, 0
	v_readlane_b32 s9, v255, 27
	s_and_b64 s[6:7], s[8:9], s[6:7]
	s_and_b64 vcc, exec, s[6:7]
	s_cbranch_vccz .LBB0_195
	v_readlane_b32 s9, v254, 20
	v_readlane_b32 s50, v254, 19
	s_mov_b32 s6, 0x3020100
	s_mov_b32 s7, 0xb0a09
	s_cmp_eq_u32 s98, 1
	s_cselect_b32 s6, 0x12111008, s6
	s_cselect_b32 s7, 0x151413, s7
	s_cmp_eq_u32 s98, 2
	s_cselect_b32 s6, 0x160c0504, s6
	s_cselect_b32 s7, 0x1a1817, s7
	s_cmp_eq_u32 s98, 3
	s_cselect_b32 s6, 0xe0d0706, s6
	s_cselect_b32 s7, 0x1b190f, s7
	s_lshl_b32 s9, s9, 3
	s_lshr_b64 s[6:7], s[6:7], s9
	s_and_b32 s99, s6, 0xff
	s_mov_b64 s[4:5], -1
